# x loads sc1 nt
# speedup vs baseline: 1.0501x; 1.0501x over previous
.LBB0_502:
	s_lshl_b32 s0, s14, 8
	s_add_i32 s4, s0, s15
	s_lshl_b32 s1, s3, 5
	v_or_b32_e32 v130, s4, v233
	s_lshl_b32 s4, s51, 8
	s_or_b32 s1, s4, s1
	v_ashrrev_i32_e32 v131, 31, v130
	v_lshl_or_b32 v128, v144, 2, s1
	v_lshlrev_b64 v[132:133], 12, v[130:131]
	v_ashrrev_i32_e32 v129, 31, v128
	v_lshl_add_u64 v[134:135], s[44:45], 0, v[132:133]
	v_lshl_add_u64 v[142:143], v[128:129], 2, v[134:135]
	s_barrier
	v_lshl_add_u32 v198, v128, 2, v132
	global_load_dwordx4 v[182:185], v198, s[44:45] sc1 nt
	global_load_dwordx4 v[186:189], v198, s[44:45] offset:64 sc1 nt
	global_load_dwordx4 v[190:193], v198, s[44:45] offset:512 sc1 nt
	global_load_dwordx4 v[194:197], v198, s[44:45] offset:576 sc1 nt
	v_add_u32_e32 v199, 0x10000, v198
	global_load_dwordx4 v[202:205], v199, s[44:45] sc1 nt
	global_load_dwordx4 v[206:209], v199, s[44:45] offset:64 sc1 nt
	global_load_dwordx4 v[210:213], v199, s[44:45] offset:512 sc1 nt
	global_load_dwordx4 v[214:217], v199, s[44:45] offset:576 sc1 nt
	v_add_u32_e32 v199, 0x20000, v198
	global_load_dwordx4 v[218:221], v199, s[44:45] sc1 nt
	global_load_dwordx4 v[222:225], v199, s[44:45] offset:64 sc1 nt
	global_load_dwordx4 v[234:237], v199, s[44:45] offset:512 sc1 nt
	global_load_dwordx4 v[238:241], v199, s[44:45] offset:576 sc1 nt
	v_mbcnt_lo_u32_b32 v142, -1, 0
	v_mbcnt_hi_u32_b32 v142, -1, v142
	v_and_b32_e32 v145, 64, v142
	v_xor_b32_e32 v143, 16, v142
	v_add_u32_e32 v145, 64, v145
	v_cmp_lt_i32_e32 vcc, v143, v145
	v_xor_b32_e32 v154, 32, v142
	s_lshl_b32 s1, s15, 2
	v_cndmask_b32_e32 v143, v142, v143, vcc
	v_lshlrev_b32_e32 v171, 2, v143
	v_cmp_lt_i32_e32 vcc, v154, v145
	s_add_i32 s1, s1, 0
	s_lshl_b32 s3, s3, 10
	s_add_i32 s1, s1, s3
	v_lshl_add_u32 v173, v233, 2, s1
	s_waitcnt vmcnt(8)
	v_pk_add_f32 v[126:127], v[126:127], v[184:185]
	v_pk_add_f32 v[124:125], v[124:125], v[182:183]
	v_pk_add_f32 v[122:123], v[122:123], v[188:189]
	v_pk_add_f32 v[120:121], v[120:121], v[186:187]
	v_pk_add_f32 v[118:119], v[118:119], v[192:193]
	v_pk_add_f32 v[116:117], v[116:117], v[190:191]
	v_mul_f32_e32 v134, v125, v125
	v_mul_f32_e32 v135, v127, v127
	v_mul_f32_e32 v136, v121, v121
	v_mul_f32_e32 v137, v123, v123
	v_pk_add_f32 v[114:115], v[114:115], v[196:197]
	v_pk_add_f32 v[112:113], v[112:113], v[194:195]
	v_add_u32_e32 v199, 0x30000, v198
	global_load_dwordx4 v[182:185], v199, s[44:45] sc1 nt
	global_load_dwordx4 v[186:189], v199, s[44:45] offset:64 sc1 nt
	global_load_dwordx4 v[190:193], v199, s[44:45] offset:512 sc1 nt
	global_load_dwordx4 v[194:197], v199, s[44:45] offset:576 sc1 nt
	v_mul_f32_e32 v138, v117, v117
	v_mul_f32_e32 v139, v119, v119
	v_fmac_f32_e32 v134, v124, v124
	v_fmac_f32_e32 v135, v126, v126
	v_fmac_f32_e32 v136, v120, v120
	v_fmac_f32_e32 v137, v122, v122
	v_mul_f32_e32 v140, v113, v113
	v_mul_f32_e32 v141, v115, v115
	v_fmac_f32_e32 v138, v116, v116
	v_fmac_f32_e32 v139, v118, v118
	v_add_f32_e32 v134, v134, v135
	v_add_f32_e32 v135, v136, v137
	v_fmac_f32_e32 v140, v112, v112
	v_fmac_f32_e32 v141, v114, v114
	v_add_f32_e32 v136, v138, v139
	v_add_f32_e32 v134, v134, v135
	v_add_f32_e32 v137, v140, v141
	v_add_f32_e32 v134, v134, v136
	v_add_f32_e32 v134, v134, v137
	ds_bpermute_b32 v135, v171, v134
	v_cndmask_b32_e32 v136, v142, v154, vcc
	v_lshlrev_b32_e32 v172, 2, v136
	v_cmp_eq_u32_e32 vcc, 0, v144
	s_waitcnt lgkmcnt(0)
	v_add_f32_e32 v134, v134, v135
	ds_bpermute_b32 v135, v172, v134
	s_and_saveexec_b64 s[4:5], vcc
	s_cbranch_execz .LBB0_504
	s_waitcnt lgkmcnt(0)
	v_add_f32_e32 v134, v134, v135
	ds_write_b32 v173, v134
.LBB0_504:
	s_or_b64 exec, exec, s[4:5]
	v_or_b32_e32 v136, 16, v130
	v_ashrrev_i32_e32 v137, 31, v136
	s_waitcnt lgkmcnt(0)
	v_lshlrev_b64 v[134:135], 12, v[136:137]
	v_lshl_add_u64 v[138:139], s[44:45], 0, v[134:135]
	v_lshl_add_u64 v[150:151], v[128:129], 2, v[138:139]
	s_nop 0
	s_waitcnt vmcnt(11)
	v_pk_add_f32 v[110:111], v[110:111], v[204:205]
	v_pk_add_f32 v[108:109], v[108:109], v[202:203]
	s_waitcnt vmcnt(10)
	v_pk_add_f32 v[106:107], v[106:107], v[208:209]
	v_pk_add_f32 v[104:105], v[104:105], v[206:207]
	s_waitcnt vmcnt(9)
	v_pk_add_f32 v[102:103], v[102:103], v[212:213]
	v_pk_add_f32 v[100:101], v[100:101], v[210:211]
	v_mul_f32_e32 v138, v109, v109
	v_mul_f32_e32 v139, v111, v111
	v_mul_f32_e32 v140, v105, v105
	v_mul_f32_e32 v141, v107, v107
	s_waitcnt vmcnt(8)
	v_pk_add_f32 v[98:99], v[98:99], v[216:217]
	v_pk_add_f32 v[96:97], v[96:97], v[214:215]
	v_add_u32_e32 v199, 0x80000, v198
	global_load_dwordx4 v[202:205], v199, s[44:45] sc1 nt
	global_load_dwordx4 v[206:209], v199, s[44:45] offset:64 sc1 nt
	global_load_dwordx4 v[210:213], v199, s[44:45] offset:512 sc1 nt
	global_load_dwordx4 v[214:217], v199, s[44:45] offset:576 sc1 nt
	v_mul_f32_e32 v142, v101, v101
	v_mul_f32_e32 v143, v103, v103
	v_fmac_f32_e32 v138, v108, v108
	v_fmac_f32_e32 v139, v110, v110
	v_fmac_f32_e32 v140, v104, v104
	v_fmac_f32_e32 v141, v106, v106
	v_mul_f32_e32 v144, v97, v97
	v_mul_f32_e32 v145, v99, v99
	v_fmac_f32_e32 v142, v100, v100
	v_fmac_f32_e32 v143, v102, v102
	v_add_f32_e32 v138, v138, v139
	v_add_f32_e32 v139, v140, v141
	v_fmac_f32_e32 v144, v96, v96
	v_fmac_f32_e32 v145, v98, v98
	v_add_f32_e32 v140, v142, v143
	v_add_f32_e32 v138, v138, v139
	v_add_f32_e32 v138, v138, v140
	v_add_f32_e32 v139, v144, v145
	v_add_f32_e32 v138, v138, v139
	ds_bpermute_b32 v139, v171, v138
	s_waitcnt lgkmcnt(0)
	v_add_f32_e32 v138, v138, v139
	ds_bpermute_b32 v139, v172, v138
	s_and_saveexec_b64 s[4:5], vcc
	s_cbranch_execz .LBB0_506
	s_waitcnt lgkmcnt(0)
	v_add_f32_e32 v138, v138, v139
	ds_write_b32 v173, v138 offset:64
.LBB0_506:
	s_or_b64 exec, exec, s[4:5]
	v_or_b32_e32 v140, 32, v130
	v_ashrrev_i32_e32 v141, 31, v140
	s_waitcnt lgkmcnt(0)
	v_lshlrev_b64 v[138:139], 12, v[140:141]
	v_lshl_add_u64 v[142:143], s[44:45], 0, v[138:139]
	v_lshl_add_u64 v[154:155], v[128:129], 2, v[142:143]
	s_nop 0
	s_waitcnt vmcnt(11)
	v_pk_add_f32 v[94:95], v[94:95], v[220:221]
	v_pk_add_f32 v[92:93], v[92:93], v[218:219]
	s_waitcnt vmcnt(10)
	v_pk_add_f32 v[90:91], v[90:91], v[224:225]
	v_pk_add_f32 v[88:89], v[88:89], v[222:223]
	s_waitcnt vmcnt(9)
	v_pk_add_f32 v[86:87], v[86:87], v[236:237]
	v_pk_add_f32 v[84:85], v[84:85], v[234:235]
	v_mul_f32_e32 v142, v93, v93
	v_mul_f32_e32 v143, v95, v95
	v_mul_f32_e32 v144, v89, v89
	v_mul_f32_e32 v145, v91, v91
	s_waitcnt vmcnt(8)
	v_pk_add_f32 v[82:83], v[82:83], v[240:241]
	v_pk_add_f32 v[80:81], v[80:81], v[238:239]
	v_add_u32_e32 v199, 0x90000, v198
	global_load_dwordx4 v[218:221], v199, s[44:45] sc1 nt
	global_load_dwordx4 v[222:225], v199, s[44:45] offset:64 sc1 nt
	global_load_dwordx4 v[234:237], v199, s[44:45] offset:512 sc1 nt
	global_load_dwordx4 v[238:241], v199, s[44:45] offset:576 sc1 nt
	v_mul_f32_e32 v146, v85, v85
	v_mul_f32_e32 v147, v87, v87
	v_fmac_f32_e32 v142, v92, v92
	v_fmac_f32_e32 v143, v94, v94
	v_fmac_f32_e32 v144, v88, v88
	v_fmac_f32_e32 v145, v90, v90
	v_mul_f32_e32 v148, v81, v81
	v_mul_f32_e32 v149, v83, v83
	v_fmac_f32_e32 v146, v84, v84
	v_fmac_f32_e32 v147, v86, v86
	v_add_f32_e32 v142, v142, v143
	v_add_f32_e32 v143, v144, v145
	v_fmac_f32_e32 v148, v80, v80
	v_fmac_f32_e32 v149, v82, v82
	v_add_f32_e32 v144, v146, v147
	v_add_f32_e32 v142, v142, v143
	v_add_f32_e32 v142, v142, v144
	v_add_f32_e32 v143, v148, v149
	v_add_f32_e32 v142, v142, v143
	ds_bpermute_b32 v143, v171, v142
	s_waitcnt lgkmcnt(0)
	v_add_f32_e32 v142, v142, v143
	ds_bpermute_b32 v143, v172, v142
	s_and_saveexec_b64 s[4:5], vcc
	s_cbranch_execz .LBB0_508
	s_waitcnt lgkmcnt(0)
	v_add_f32_e32 v142, v142, v143
	ds_write_b32 v173, v142 offset:128
.LBB0_508:
	s_or_b64 exec, exec, s[4:5]
	v_or_b32_e32 v144, 48, v130
	v_ashrrev_i32_e32 v145, 31, v144
	s_waitcnt lgkmcnt(0)
	v_lshlrev_b64 v[142:143], 12, v[144:145]
	v_lshl_add_u64 v[146:147], s[44:45], 0, v[142:143]
	v_lshl_add_u64 v[158:159], v[128:129], 2, v[146:147]
	s_nop 0
	s_waitcnt vmcnt(11)
	v_pk_add_f32 v[78:79], v[78:79], v[184:185]
	v_pk_add_f32 v[146:147], v[76:77], v[182:183]
	s_waitcnt vmcnt(10)
	v_pk_add_f32 v[74:75], v[74:75], v[188:189]
	v_pk_add_f32 v[76:77], v[72:73], v[186:187]
	s_waitcnt vmcnt(9)
	v_pk_add_f32 v[70:71], v[70:71], v[192:193]
	v_pk_add_f32 v[68:69], v[68:69], v[190:191]
	v_mul_f32_e32 v72, v147, v147
	v_mul_f32_e32 v73, v79, v79
	v_mul_f32_e32 v148, v77, v77
	v_mul_f32_e32 v149, v75, v75
	s_waitcnt vmcnt(8)
	v_pk_add_f32 v[66:67], v[66:67], v[196:197]
	v_pk_add_f32 v[64:65], v[64:65], v[194:195]
	v_add_u32_e32 v199, 0xa0000, v198
	global_load_dwordx4 v[182:185], v199, s[44:45] sc1 nt
	global_load_dwordx4 v[186:189], v199, s[44:45] offset:64 sc1 nt
	global_load_dwordx4 v[190:193], v199, s[44:45] offset:512 sc1 nt
	global_load_dwordx4 v[194:197], v199, s[44:45] offset:576 sc1 nt
	v_mul_f32_e32 v150, v69, v69
	v_mul_f32_e32 v151, v71, v71
	v_fmac_f32_e32 v72, v146, v146
	v_fmac_f32_e32 v73, v78, v78
	v_fmac_f32_e32 v148, v76, v76
	v_fmac_f32_e32 v149, v74, v74
	v_mul_f32_e32 v152, v65, v65
	v_mul_f32_e32 v153, v67, v67
	v_fmac_f32_e32 v150, v68, v68
	v_fmac_f32_e32 v151, v70, v70
	v_add_f32_e32 v72, v72, v73
	v_add_f32_e32 v73, v148, v149
	v_fmac_f32_e32 v152, v64, v64
	v_fmac_f32_e32 v153, v66, v66
	v_add_f32_e32 v148, v150, v151
	v_add_f32_e32 v72, v72, v73
	v_add_f32_e32 v72, v72, v148
	v_add_f32_e32 v73, v152, v153
	v_add_f32_e32 v72, v72, v73
	ds_bpermute_b32 v73, v171, v72
	s_waitcnt lgkmcnt(0)
	v_add_f32_e32 v72, v72, v73
	ds_bpermute_b32 v73, v172, v72
	s_and_saveexec_b64 s[4:5], vcc
	s_cbranch_execz .LBB0_510
	s_waitcnt lgkmcnt(0)
	v_add_f32_e32 v72, v72, v73
	ds_write_b32 v173, v72 offset:192
.LBB0_510:
	s_or_b64 exec, exec, s[4:5]
	s_mov_b64 s[4:5], 0x80000
	s_waitcnt lgkmcnt(0)
	v_lshl_add_u64 v[72:73], v[132:133], 0, s[4:5]
	v_lshl_add_u64 v[148:149], s[44:45], 0, v[72:73]
	v_lshl_add_u64 v[160:161], v[128:129], 2, v[148:149]
	s_nop 0
	s_waitcnt vmcnt(11)
	v_pk_add_f32 v[62:63], v[62:63], v[204:205]
	v_pk_add_f32 v[148:149], v[60:61], v[202:203]
	s_waitcnt vmcnt(10)
	v_pk_add_f32 v[58:59], v[58:59], v[208:209]
	v_pk_add_f32 v[60:61], v[56:57], v[206:207]
	s_waitcnt vmcnt(9)
	v_pk_add_f32 v[54:55], v[54:55], v[212:213]
	v_pk_add_f32 v[52:53], v[52:53], v[210:211]
	v_mul_f32_e32 v56, v149, v149
	v_mul_f32_e32 v57, v63, v63
	v_mul_f32_e32 v150, v61, v61
	v_mul_f32_e32 v151, v59, v59
	s_waitcnt vmcnt(8)
	v_pk_add_f32 v[50:51], v[50:51], v[216:217]
	v_pk_add_f32 v[48:49], v[48:49], v[214:215]
	v_add_u32_e32 v199, 0xb0000, v198
	global_load_dwordx4 v[202:205], v199, s[44:45] sc1 nt
	global_load_dwordx4 v[206:209], v199, s[44:45] offset:64 sc1 nt
	global_load_dwordx4 v[210:213], v199, s[44:45] offset:512 sc1 nt
	global_load_dwordx4 v[214:217], v199, s[44:45] offset:576 sc1 nt
	v_mul_f32_e32 v152, v53, v53
	v_mul_f32_e32 v153, v55, v55
	v_fmac_f32_e32 v56, v148, v148
	v_fmac_f32_e32 v57, v62, v62
	v_fmac_f32_e32 v150, v60, v60
	v_fmac_f32_e32 v151, v58, v58
	v_mul_f32_e32 v154, v49, v49
	v_mul_f32_e32 v155, v51, v51
	v_fmac_f32_e32 v152, v52, v52
	v_fmac_f32_e32 v153, v54, v54
	v_add_f32_e32 v56, v56, v57
	v_add_f32_e32 v57, v150, v151
	v_fmac_f32_e32 v154, v48, v48
	v_fmac_f32_e32 v155, v50, v50
	v_add_f32_e32 v150, v152, v153
	v_add_f32_e32 v56, v56, v57
	v_add_f32_e32 v56, v56, v150
	v_add_f32_e32 v57, v154, v155
	v_add_f32_e32 v56, v56, v57
	ds_bpermute_b32 v57, v171, v56
	s_waitcnt lgkmcnt(0)
	v_add_f32_e32 v56, v56, v57
	ds_bpermute_b32 v57, v172, v56
	s_and_saveexec_b64 s[4:5], vcc
	s_cbranch_execz .LBB0_512
	s_waitcnt lgkmcnt(0)
	v_add_f32_e32 v56, v56, v57
	ds_write_b32 v173, v56 offset:512
